# waitcnt placement: DSA sparse attention reads all eight QK fragments up front, MFMAs behind counted lgkmcnt waits
# speedup vs baseline: 1.0018x; 1.0018x over previous
; DI f32x16 mfma32(bf16x8 a, bf16x8 b, f32x16 c) { return __builtin_amdgcn_mfma_f32_32x32x16_bf16(a, b, c, 0, 0, 0); }
; DI int crow(int i, int hh) { return (i & 3) + 8 * (i >> 2) + 4 * hh; }
; DI void dsa_item(const Params& p, int l, int tile32, int b, char* smem) {
;     ...
;       f32x16 sa;
; #pragma unroll
;       for (int j = 0; j < 16; ++j) sa[j] = 0.f;
; #pragma unroll
;       for (int s = 0; s < 8; ++s) sa = mfma32(*(const bf16x8*)(tile + c31 * 272 + (16 * s + 8 * hh) * 2), qf[s], sa);
;       float tmax = -INFINITY;
; #pragma unroll
;       for (int j = 0; j < 16; ++j) {
;         if (tt * 32 + crow(j, hh) >= nsel) sa[j] = -INFINITY;
;         tmax = fmaxf(tmax, sa[j]);
;       }
;       tmax = xhalf_max(tmax);
;       const float cand = tmax * sc;
;       if (__any(cand > mrun + 8.f)) {
;         const float mnew = fmaxf(mrun, cand);
;         const float alpha = __builtin_amdgcn_exp2f(mrun - mnew);
;         mrun = mnew;
;         lrun *= alpha;
; #pragma unroll
;         for (int i = 0; i < 4; ++i)
; #pragma unroll
;           for (int j = 0; j < 16; ++j) O[i][j] *= alpha;
;       }
.LBB0_569:
	s_or_b64 exec, exec, s[2:3]
	ds_read_b128 v[2:5], v208
	ds_read_b128 v[6:9], v208 offset:32
	ds_read_b128 v[226:229], v208 offset:64
	ds_read_b128 v[230:233], v208 offset:96
	ds_read_b128 v[234:237], v208 offset:128
	ds_read_b128 v[238:241], v208 offset:160
	ds_read_b128 v[242:245], v208 offset:192
	ds_read_b128 v[246:249], v208 offset:224
	v_subrev_u32_e32 v0, 27, v210
	v_cmp_lt_i32_e32 vcc, v0, v177
	s_waitcnt lgkmcnt(7)
	v_mfma_f32_32x32x16_bf16 v[80:95], v[2:5], v[128:131], 0
	s_mov_b32 s4, 0xff800000
	v_add_u32_e32 v10, -10, v210
	v_cmp_lt_i32_e64 s[18:19], v10, v177
	v_add_u32_e32 v12, -8, v210
	v_cmp_lt_i32_e64 s[22:23], v12, v177
	v_add_u32_e32 v14, -2, v210
	s_waitcnt lgkmcnt(6)
	v_mfma_f32_32x32x16_bf16 v[80:95], v[6:9], v[132:135], v[80:95]
	v_subrev_u32_e32 v6, 18, v210
	v_cmp_lt_i32_e64 s[10:11], v6, v177
	v_add_u32_e32 v8, -16, v210
	v_cmp_lt_i32_e64 s[14:15], v8, v177
	v_cmp_lt_i32_e64 s[26:27], v14, v177
	v_cmp_lt_i32_e64 s[30:31], v210, v177
	s_waitcnt lgkmcnt(5)
	v_mfma_f32_32x32x16_bf16 v[80:95], v[226:229], v[136:139], v[80:95]
	s_waitcnt lgkmcnt(4)
	v_mfma_f32_32x32x16_bf16 v[80:95], v[230:233], v[140:143], v[80:95]
	s_waitcnt lgkmcnt(3)
	v_mfma_f32_32x32x16_bf16 v[80:95], v[234:237], v[144:147], v[80:95]
	s_waitcnt lgkmcnt(2)
	v_mfma_f32_32x32x16_bf16 v[80:95], v[238:241], v[148:151], v[80:95]
	s_waitcnt lgkmcnt(1)
	v_mfma_f32_32x32x16_bf16 v[80:95], v[242:245], v[152:155], v[80:95]
	s_waitcnt lgkmcnt(0)
	v_mfma_f32_32x32x16_bf16 v[80:95], v[246:249], v[156:159], v[80:95]
	v_subrev_u32_e32 v2, 26, v210
	v_cmp_lt_i32_e64 s[2:3], v2, v177
	v_subrev_u32_e32 v3, 25, v210
	v_subrev_u32_e32 v4, 24, v210
	v_cmp_lt_i32_e64 s[6:7], v4, v177
	s_nop 6
	v_cndmask_b32_e32 v0, v205, v80, vcc
	v_cndmask_b32_e64 v2, v205, v81, s[2:3]
	v_max3_f32 v5, v0, s4, v2
	v_cmp_lt_i32_e64 s[4:5], v3, v177
	v_cndmask_b32_e64 v4, v205, v83, s[6:7]
	v_cndmask_b32_e64 v6, v205, v85, s[10:11]
	v_cndmask_b32_e64 v3, v205, v82, s[4:5]
	v_max3_f32 v7, v5, v3, v4
	v_subrev_u32_e32 v5, 19, v210
	v_cmp_lt_i32_e64 s[8:9], v5, v177
	v_cndmask_b32_e64 v8, v205, v87, s[14:15]
	v_cndmask_b32_e64 v10, v205, v89, s[18:19]
	v_cndmask_b32_e64 v5, v205, v84, s[8:9]
	v_max3_f32 v9, v7, v5, v6
	v_subrev_u32_e32 v7, 17, v210
	v_cmp_lt_i32_e64 s[12:13], v7, v177
	v_cndmask_b32_e64 v12, v205, v91, s[22:23]
	v_cndmask_b32_e64 v14, v205, v93, s[26:27]
	v_cndmask_b32_e64 v7, v205, v86, s[12:13]
	v_max3_f32 v11, v9, v7, v8
	v_add_u32_e32 v9, -11, v210
	v_cmp_lt_i32_e64 s[16:17], v9, v177
	s_nop 1
	v_cndmask_b32_e64 v9, v205, v88, s[16:17]
	v_max3_f32 v13, v11, v9, v10
	v_add_u32_e32 v11, -9, v210
	v_cmp_lt_i32_e64 s[20:21], v11, v177
	s_nop 1
	v_cndmask_b32_e64 v11, v205, v90, s[20:21]
	v_max3_f32 v15, v13, v11, v12
	v_add_u32_e32 v13, -3, v210
	v_cmp_lt_i32_e64 s[24:25], v13, v177
	s_nop 1
	v_cndmask_b32_e64 v13, v205, v92, s[24:25]
	v_max3_f32 v213, v15, v13, v14
	v_add_u32_e32 v15, -1, v210
	v_cmp_lt_i32_e64 s[28:29], v15, v177
	v_cndmask_b32_e64 v15, v205, v95, s[30:31]
	s_nop 0
	v_cndmask_b32_e64 v212, v205, v94, s[28:29]
	v_max3_f32 v95, v213, v212, v15
	v_mov_b32_e32 v213, v95
	s_nop 1
	v_permlane32_swap_b32_e32 v95, v213
	v_max_f32_e32 v213, v213, v213
	v_max_f32_e32 v95, v95, v95
	v_max_f32_e32 v95, v95, v213
	v_mul_f32_e32 v95, 0x3e38aa3b, v95
	v_add_f32_e32 v213, 0x41000000, v211
	v_cmp_gt_f32_e32 vcc, v95, v213
	s_cbranch_vccz .LBB0_566
	v_max_f32_e32 v95, v95, v95
	v_max_f32_e32 v213, v211, v211
	v_max_f32_e32 v95, v213, v95
	v_sub_f32_e32 v211, v211, v95
	v_exp_f32_e32 v214, v211
	v_mov_b32_e32 v211, v95
	v_pk_mul_f32 v[78:79], v[78:79], v[214:215] op_sel_hi:[1,0]
	v_pk_mul_f32 v[76:77], v[76:77], v[214:215] op_sel_hi:[1,0]
	v_pk_mul_f32 v[74:75], v[74:75], v[214:215] op_sel_hi:[1,0]
	v_pk_mul_f32 v[72:73], v[72:73], v[214:215] op_sel_hi:[1,0]
	v_pk_mul_f32 v[70:71], v[70:71], v[214:215] op_sel_hi:[1,0]
	v_pk_mul_f32 v[68:69], v[68:69], v[214:215] op_sel_hi:[1,0]
	v_pk_mul_f32 v[66:67], v[66:67], v[214:215] op_sel_hi:[1,0]
	v_pk_mul_f32 v[64:65], v[64:65], v[214:215] op_sel_hi:[1,0]
	v_pk_mul_f32 v[62:63], v[62:63], v[214:215] op_sel_hi:[1,0]
	v_pk_mul_f32 v[60:61], v[60:61], v[214:215] op_sel_hi:[1,0]
	v_pk_mul_f32 v[58:59], v[58:59], v[214:215] op_sel_hi:[1,0]
	v_pk_mul_f32 v[56:57], v[56:57], v[214:215] op_sel_hi:[1,0]
	v_pk_mul_f32 v[54:55], v[54:55], v[214:215] op_sel_hi:[1,0]
	v_pk_mul_f32 v[52:53], v[52:53], v[214:215] op_sel_hi:[1,0]
	v_pk_mul_f32 v[50:51], v[50:51], v[214:215] op_sel_hi:[1,0]
	v_pk_mul_f32 v[48:49], v[48:49], v[214:215] op_sel_hi:[1,0]
	v_pk_mul_f32 v[46:47], v[46:47], v[214:215] op_sel_hi:[1,0]
	v_pk_mul_f32 v[44:45], v[44:45], v[214:215] op_sel_hi:[1,0]
	v_pk_mul_f32 v[42:43], v[42:43], v[214:215] op_sel_hi:[1,0]
	v_pk_mul_f32 v[40:41], v[40:41], v[214:215] op_sel_hi:[1,0]
	v_pk_mul_f32 v[38:39], v[38:39], v[214:215] op_sel_hi:[1,0]
	v_pk_mul_f32 v[36:37], v[36:37], v[214:215] op_sel_hi:[1,0]
	v_pk_mul_f32 v[34:35], v[34:35], v[214:215] op_sel_hi:[1,0]
	v_pk_mul_f32 v[32:33], v[32:33], v[214:215] op_sel_hi:[1,0]
	v_pk_mul_f32 v[30:31], v[30:31], v[214:215] op_sel_hi:[1,0]
	v_pk_mul_f32 v[28:29], v[28:29], v[214:215] op_sel_hi:[1,0]
	v_pk_mul_f32 v[26:27], v[26:27], v[214:215] op_sel_hi:[1,0]
	v_pk_mul_f32 v[24:25], v[24:25], v[214:215] op_sel_hi:[1,0]
	v_pk_mul_f32 v[22:23], v[22:23], v[214:215] op_sel_hi:[1,0]
	v_pk_mul_f32 v[20:21], v[20:21], v[214:215] op_sel_hi:[1,0]
	v_pk_mul_f32 v[18:19], v[18:19], v[214:215] op_sel_hi:[1,0]
	v_pk_mul_f32 v[16:17], v[16:17], v[214:215] op_sel_hi:[1,0]
	v_mul_f32_e32 v165, v165, v214
	s_branch .LBB0_566
